# fast path: each V fragment read as two ds_read_b64 with immediate offsets (256 B/clk class) instead of ds_read2_b64; no per-iteration V base adds
# baseline (speedup 1.0000x reference)
; DI void attn_item(const Params& p, int l, int item, char* lds) {
;     ...
;     f32x16 s[2];
; #pragma unroll
;     for (int kt = 0; kt < 2; ++kt) {
; #pragma unroll
;       for (int e = 0; e < 16; ++e) s[kt][e] = 0.f;
; #pragma unroll
;       for (int ks = 0; ks < 4; ++ks) {
;         const bf16x8 kf = *(const bf16x8*)(Ks + (m * 64 + kt * 32 + q) * ALD + ks * 16 + hh * 8);
;         s[kt] = __builtin_amdgcn_mfma_f32_32x32x16_bf16(kf, qf[ks], s[kt], 0, 0, 0);
;       }
;     }
;     float mx = -1e30f;
;     const float dbase = qposf - (float)(j * 64 + 4 * hh);
; #pragma unroll
;     for (int kt = 0; kt < 2; ++kt)
; #pragma unroll
;       for (int e = 0; e < 16; ++e) {
;         const float dd = dbase - (float)(kt * 32 + (e & 3) + 8 * (e >> 2));
;         const float v = s[kt][e] * c1 - sl2 * fabsf(dd);
;         s[kt][e] = v; mx = fmaxf(mx, v);
;       }
;     mx = fmaxf(mx, __shfl_xor(mx, 32));
;     const float mnew = fmaxf(mrun, mx);
;     const float alpha = __builtin_amdgcn_exp2f(mrun - mnew);
;     const bool resc = mnew > mrun;
;     mrun = mnew;
;     float ps = 0.f;
; #pragma unroll
;     for (int kt = 0; kt < 2; ++kt)
; #pragma unroll
;       for (int e = 0; e < 16; ++e) { const float pe = __builtin_amdgcn_exp2f(s[kt][e] - mnew); s[kt][e] = pe; ps += pe; }
;     lrun = lrun * alpha + ps;
;     if (__any(resc)) {
; #pragma unroll
;       for (int i = 0; i < 4; ++i)
; #pragma unroll
;         for (int e = 0; e < 16; ++e) O[i][e] *= alpha;
;     }
.Lfa_body:
	ds_read_b128 v[2:5], v202
	ds_read_b128 v[6:9], v202 offset:32
	ds_read_b128 v[10:13], v202 offset:64
	ds_read_b128 v[222:225], v202 offset:96
	ds_read_b128 v[226:229], v202 offset:4608
	v_mfma_f32_32x32x8_bf16 v[96:111], v[206:207], v[214:215], 0
	v_mfma_f32_32x32x8_bf16 v[80:95], v[206:207], v[216:217], 0
	s_waitcnt lgkmcnt(4)
	v_mfma_f32_32x32x16_bf16 v[96:111], v[2:5], v[120:123], v[96:111]
	ds_read_b128 v[2:5], v202 offset:4640
	s_waitcnt lgkmcnt(4)
	v_mfma_f32_32x32x16_bf16 v[96:111], v[6:9], v[112:115], v[96:111]
	ds_read_b128 v[6:9], v202 offset:4672
	s_waitcnt lgkmcnt(4)
	v_mfma_f32_32x32x16_bf16 v[96:111], v[10:13], v[116:119], v[96:111]
	ds_read_b128 v[10:13], v202 offset:4704
	s_waitcnt lgkmcnt(4)
	v_mfma_f32_32x32x16_bf16 v[96:111], v[222:225], v[124:127], v[96:111]
	s_waitcnt lgkmcnt(3)
	v_mfma_f32_32x32x16_bf16 v[80:95], v[226:229], v[120:123], v[80:95]
	s_waitcnt lgkmcnt(2)
	v_mfma_f32_32x32x16_bf16 v[80:95], v[2:5], v[112:115], v[80:95]
	s_waitcnt lgkmcnt(1)
	v_mfma_f32_32x32x16_bf16 v[80:95], v[6:9], v[116:119], v[80:95]
	s_waitcnt lgkmcnt(0)
	v_mfma_f32_32x32x16_bf16 v[80:95], v[10:13], v[124:127], v[80:95]
	ds_read_b64 v[222:223], v201 offset:32256
	ds_read_b64 v[224:225], v201 offset:32272
	ds_read_b64 v[226:227], v201 offset:18464
	ds_read_b64 v[228:229], v201 offset:18480
	s_lshl_b32 s2, s93, 6
	s_sub_i32 s2, s2, 64
	v_cvt_f32_u32_e32 v14, s2
	v_sub_f32_e32 v14, v187, v14
	v_mul_f32_e32 v14, v189, v14
	ds_read_b64 v[2:3], v201 offset:18432
	ds_read_b64 v[4:5], v201 offset:18448
	ds_read_b64 v[6:7], v201 offset:23040
	ds_read_b64 v[8:9], v201 offset:23056
	ds_read_b64 v[10:11], v201 offset:27648
	ds_read_b64 v[12:13], v201 offset:27664
	v_max3_f32 v0, v96, v97, v98
	v_max3_f32 v15, v80, v81, v82
	v_max3_f32 v0, v0, v99, v100
	v_max3_f32 v15, v15, v83, v84
	v_max3_f32 v0, v0, v101, v102
	v_max3_f32 v15, v15, v85, v86
	v_max3_f32 v0, v0, v103, v104
	v_max3_f32 v15, v15, v87, v88
	v_max3_f32 v0, v0, v105, v106
	v_max3_f32 v15, v15, v89, v90
	v_max3_f32 v0, v0, v107, v108
	v_max3_f32 v15, v15, v91, v92
	v_max3_f32 v0, v0, v109, v110
	v_max3_f32 v15, v15, v93, v94
	v_max_f32_e32 v0, v0, v111
	v_max_f32_e32 v15, v15, v95
	v_max_f32_e32 v0, v0, v15
	v_mov_b32_e32 v15, v0
	s_nop 1
	v_permlane32_swap_b32_e32 v15, v0
	s_nop 1
	v_max_f32_e32 v0, v0, v15
	v_fma_f32 v0, v0, s35, -v14
	v_sub_f32_e32 v15, v0, v204
	v_cmp_lt_f32_e32 vcc, 0x41000000, v15
	s_nop 1
	v_cndmask_b32_e32 v15, v204, v0, vcc
	v_sub_f32_e32 v0, v204, v15
	v_exp_f32_e32 v0, v0
	v_mov_b32_e32 v204, v15
	v_add_f32_e32 v14, v15, v14
	s_cbranch_vccz .Lfa_keep
	v_pk_mul_f32 v[78:79], v[78:79], v[0:1] op_sel_hi:[1,0]
	v_pk_mul_f32 v[76:77], v[76:77], v[0:1] op_sel_hi:[1,0]
	v_pk_mul_f32 v[74:75], v[74:75], v[0:1] op_sel_hi:[1,0]
	v_pk_mul_f32 v[72:73], v[72:73], v[0:1] op_sel_hi:[1,0]
	v_pk_mul_f32 v[70:71], v[70:71], v[0:1] op_sel_hi:[1,0]
	v_pk_mul_f32 v[68:69], v[68:69], v[0:1] op_sel_hi:[1,0]
	v_pk_mul_f32 v[66:67], v[66:67], v[0:1] op_sel_hi:[1,0]
	v_pk_mul_f32 v[64:65], v[64:65], v[0:1] op_sel_hi:[1,0]
	v_pk_mul_f32 v[62:63], v[62:63], v[0:1] op_sel_hi:[1,0]
	v_pk_mul_f32 v[60:61], v[60:61], v[0:1] op_sel_hi:[1,0]
	v_pk_mul_f32 v[58:59], v[58:59], v[0:1] op_sel_hi:[1,0]
	v_pk_mul_f32 v[56:57], v[56:57], v[0:1] op_sel_hi:[1,0]
	v_pk_mul_f32 v[54:55], v[54:55], v[0:1] op_sel_hi:[1,0]
	v_pk_mul_f32 v[52:53], v[52:53], v[0:1] op_sel_hi:[1,0]
	v_pk_mul_f32 v[50:51], v[50:51], v[0:1] op_sel_hi:[1,0]
	v_pk_mul_f32 v[48:49], v[48:49], v[0:1] op_sel_hi:[1,0]
	v_pk_mul_f32 v[46:47], v[46:47], v[0:1] op_sel_hi:[1,0]
	v_pk_mul_f32 v[44:45], v[44:45], v[0:1] op_sel_hi:[1,0]
	v_pk_mul_f32 v[42:43], v[42:43], v[0:1] op_sel_hi:[1,0]
	v_pk_mul_f32 v[40:41], v[40:41], v[0:1] op_sel_hi:[1,0]
	v_pk_mul_f32 v[38:39], v[38:39], v[0:1] op_sel_hi:[1,0]
	v_pk_mul_f32 v[36:37], v[36:37], v[0:1] op_sel_hi:[1,0]
	v_pk_mul_f32 v[34:35], v[34:35], v[0:1] op_sel_hi:[1,0]
	v_pk_mul_f32 v[32:33], v[32:33], v[0:1] op_sel_hi:[1,0]
	v_pk_mul_f32 v[30:31], v[30:31], v[0:1] op_sel_hi:[1,0]
	v_pk_mul_f32 v[28:29], v[28:29], v[0:1] op_sel_hi:[1,0]
	v_pk_mul_f32 v[26:27], v[26:27], v[0:1] op_sel_hi:[1,0]
	v_pk_mul_f32 v[24:25], v[24:25], v[0:1] op_sel_hi:[1,0]
	v_pk_mul_f32 v[22:23], v[22:23], v[0:1] op_sel_hi:[1,0]
	v_pk_mul_f32 v[20:21], v[20:21], v[0:1] op_sel_hi:[1,0]
	v_pk_mul_f32 v[18:19], v[18:19], v[0:1] op_sel_hi:[1,0]
	v_pk_mul_f32 v[16:17], v[16:17], v[0:1] op_sel_hi:[1,0]
; DI unsigned pk2(float a, float b) { f32x2 v = {a, b}; bfv2 r = __builtin_convertvector(v, bfv2); return __builtin_bit_cast(unsigned, r); }
; DI void attn_item(const Params& p, int l, int item, char* lds) {
;     ...
; #pragma unroll
;     for (int kt = 0; kt < 2; ++kt)
; #pragma unroll
;       for (int e = 0; e < 16; ++e) { const float pe = __builtin_amdgcn_exp2f(s[kt][e] - mnew); s[kt][e] = pe; ps += pe; }
;     lrun = lrun * alpha + ps;
;     if (__any(resc)) {
; #pragma unroll
;       for (int i = 0; i < 4; ++i)
; #pragma unroll
;         for (int e = 0; e < 16; ++e) O[i][e] *= alpha;
;     }
; #pragma unroll
;     for (int kt = 0; kt < 2; ++kt)
; #pragma unroll
;       for (int sx = 0; sx < 2; ++sx) {
;         u32x4 pb;
;         pb[0] = pk2(s[kt][8 * sx + 0], s[kt][8 * sx + 1]); pb[1] = pk2(s[kt][8 * sx + 2], s[kt][8 * sx + 3]);
;         pb[2] = pk2(s[kt][8 * sx + 4], s[kt][8 * sx + 5]); pb[3] = pk2(s[kt][8 * sx + 6], s[kt][8 * sx + 7]);
;         const bf16x8 pf = __builtin_bit_cast(bf16x8, pb);
; #pragma unroll
;         for (int vt = 0; vt < 4; ++vt) {
;           const bf16_t* vp = Vs + (vt * 32 + q) * ALD + kt * 32 + 16 * sx + 4 * hh;
;           const s16x4 lo = *(const s16x4*)vp, hi = *(const s16x4*)(vp + 8);
;           const bf16x8 vf = __builtin_shufflevector(lo, hi, 0, 1, 2, 3, 4, 5, 6, 7);
;           O[vt] = __builtin_amdgcn_mfma_f32_32x32x16_bf16(vf, pf, O[vt], 0, 0, 0);
;         }
;       }
;     __syncthreads();
;     if (j + 1 < nch) sstore();
;     __syncthreads();
.Lfa_keep:
	v_fma_f32 v96, v96, s35, -v14
	v_fma_f32 v97, v97, s35, -v14
	v_fma_f32 v98, v98, s35, -v14
	v_fma_f32 v99, v99, s35, -v14
	v_fma_f32 v100, v100, s35, -v14
	v_fma_f32 v101, v101, s35, -v14
	v_fma_f32 v102, v102, s35, -v14
	v_fma_f32 v103, v103, s35, -v14
	v_exp_f32_e32 v96, v96
	v_exp_f32_e32 v97, v97
	v_exp_f32_e32 v98, v98
	v_exp_f32_e32 v99, v99
	v_exp_f32_e32 v100, v100
	v_exp_f32_e32 v101, v101
	v_exp_f32_e32 v102, v102
	v_exp_f32_e32 v103, v103
	v_add_f32_e32 v15, v96, v98
	v_add_f32_e32 v205, v97, v99
	v_add_f32_e32 v15, v15, v100
	v_add_f32_e32 v205, v205, v101
	v_add_f32_e32 v15, v15, v102
	v_add_f32_e32 v205, v205, v103
	v_cvt_pk_bf16_f32 v96, v96, v97
	v_cvt_pk_bf16_f32 v97, v98, v99
	v_cvt_pk_bf16_f32 v98, v100, v101
	v_cvt_pk_bf16_f32 v99, v102, v103
	v_fma_f32 v104, v104, s35, -v14
	v_fma_f32 v105, v105, s35, -v14
	s_waitcnt lgkmcnt(4)
	v_mfma_f32_32x32x16_bf16 v[64:79], v[2:5], v[96:99], v[64:79]
	ds_read_b64 v[2:3], v201 offset:23072
	ds_read_b64 v[4:5], v201 offset:23088
	v_fma_f32 v106, v106, s35, -v14
	v_fma_f32 v107, v107, s35, -v14
	v_fma_f32 v108, v108, s35, -v14
	v_fma_f32 v109, v109, s35, -v14
	v_fma_f32 v110, v110, s35, -v14
	v_fma_f32 v111, v111, s35, -v14
	v_exp_f32_e32 v104, v104
	s_waitcnt lgkmcnt(4)
	v_mfma_f32_32x32x16_bf16 v[48:63], v[6:9], v[96:99], v[48:63]
	ds_read_b64 v[6:7], v201 offset:27680
	ds_read_b64 v[8:9], v201 offset:27696
	v_exp_f32_e32 v105, v105
	v_exp_f32_e32 v106, v106
	v_exp_f32_e32 v107, v107
	v_exp_f32_e32 v108, v108
	v_exp_f32_e32 v109, v109
	v_exp_f32_e32 v110, v110
	v_exp_f32_e32 v111, v111
	s_waitcnt lgkmcnt(4)
	v_mfma_f32_32x32x16_bf16 v[32:47], v[10:13], v[96:99], v[32:47]
	ds_read_b64 v[10:11], v201 offset:32288
	ds_read_b64 v[12:13], v201 offset:32304
	v_add_f32_e32 v15, v15, v104
	v_add_f32_e32 v205, v205, v105
	v_add_f32_e32 v15, v15, v106
	v_add_f32_e32 v205, v205, v107
	v_add_f32_e32 v15, v15, v108
	v_add_f32_e32 v205, v205, v109
	v_add_f32_e32 v15, v15, v110
	s_waitcnt lgkmcnt(14)
	v_mfma_f32_32x32x16_bf16 v[16:31], v[222:225], v[96:99], v[16:31]
	ds_read_b64 v[222:223], v201 offset:18496
	ds_read_b64 v[224:225], v201 offset:18512
	v_add_f32_e32 v205, v205, v111
	v_cvt_pk_bf16_f32 v104, v104, v105
	v_cvt_pk_bf16_f32 v105, v106, v107
	v_cvt_pk_bf16_f32 v106, v108, v109
	v_cvt_pk_bf16_f32 v107, v110, v111
	v_fma_f32 v80, v80, s35, -v14
	v_fma_f32 v81, v81, s35, -v14
	s_waitcnt lgkmcnt(14)
	v_mfma_f32_32x32x16_bf16 v[64:79], v[226:229], v[104:107], v[64:79]
	ds_read_b64 v[226:227], v201 offset:23104
	ds_read_b64 v[228:229], v201 offset:23120
	v_fma_f32 v82, v82, s35, -v14
	v_fma_f32 v83, v83, s35, -v14
	v_fma_f32 v84, v84, s35, -v14
	v_fma_f32 v85, v85, s35, -v14
	v_fma_f32 v86, v86, s35, -v14
	v_fma_f32 v87, v87, s35, -v14
	v_exp_f32_e32 v80, v80
	s_waitcnt lgkmcnt(8)
	v_mfma_f32_32x32x16_bf16 v[48:63], v[2:5], v[104:107], v[48:63]
	ds_read_b64 v[2:3], v201 offset:27712
	ds_read_b64 v[4:5], v201 offset:27728
	v_exp_f32_e32 v81, v81
	v_exp_f32_e32 v82, v82
	v_exp_f32_e32 v83, v83
	v_exp_f32_e32 v84, v84
	v_exp_f32_e32 v85, v85
	v_exp_f32_e32 v86, v86
	v_exp_f32_e32 v87, v87
	s_waitcnt lgkmcnt(8)
	v_mfma_f32_32x32x16_bf16 v[32:47], v[6:9], v[104:107], v[32:47]
	ds_read_b64 v[6:7], v201 offset:32320
	ds_read_b64 v[8:9], v201 offset:32336
	v_add_f32_e32 v15, v15, v80
	v_add_f32_e32 v205, v205, v81
	v_add_f32_e32 v15, v15, v82
	v_add_f32_e32 v205, v205, v83
	v_add_f32_e32 v15, v15, v84
	v_add_f32_e32 v205, v205, v85
	v_add_f32_e32 v15, v15, v86
	s_waitcnt lgkmcnt(8)
	v_mfma_f32_32x32x16_bf16 v[16:31], v[10:13], v[104:107], v[16:31]
	ds_read_b64 v[10:11], v201 offset:18528
	ds_read_b64 v[12:13], v201 offset:18544
	v_add_f32_e32 v205, v205, v87
	v_cvt_pk_bf16_f32 v80, v80, v81
	v_cvt_pk_bf16_f32 v81, v82, v83
	v_cvt_pk_bf16_f32 v82, v84, v85
	v_cvt_pk_bf16_f32 v83, v86, v87
	v_fma_f32 v88, v88, s35, -v14
	v_fma_f32 v89, v89, s35, -v14
	s_waitcnt lgkmcnt(8)
	v_mfma_f32_32x32x16_bf16 v[64:79], v[222:225], v[80:83], v[64:79]
	ds_read_b64 v[222:223], v201 offset:23136
	ds_read_b64 v[224:225], v201 offset:23152
	v_fma_f32 v90, v90, s35, -v14
	v_fma_f32 v91, v91, s35, -v14
	v_fma_f32 v92, v92, s35, -v14
	v_fma_f32 v93, v93, s35, -v14
	v_fma_f32 v94, v94, s35, -v14
	v_fma_f32 v95, v95, s35, -v14
	v_exp_f32_e32 v88, v88
	s_waitcnt lgkmcnt(8)
	v_mfma_f32_32x32x16_bf16 v[48:63], v[226:229], v[80:83], v[48:63]
	ds_read_b64 v[226:227], v201 offset:27744
	ds_read_b64 v[228:229], v201 offset:27760
	v_exp_f32_e32 v89, v89
	v_exp_f32_e32 v90, v90
	v_exp_f32_e32 v91, v91
	v_exp_f32_e32 v92, v92
	v_exp_f32_e32 v93, v93
	v_exp_f32_e32 v94, v94
	v_exp_f32_e32 v95, v95
	s_waitcnt lgkmcnt(8)
	v_mfma_f32_32x32x16_bf16 v[32:47], v[2:5], v[80:83], v[32:47]
	ds_read_b64 v[2:3], v201 offset:32352
	ds_read_b64 v[4:5], v201 offset:32368
	v_add_f32_e32 v15, v15, v88
	v_add_f32_e32 v205, v205, v89
	v_add_f32_e32 v15, v15, v90
	v_add_f32_e32 v205, v205, v91
	v_add_f32_e32 v15, v15, v92
	v_add_f32_e32 v205, v205, v93
	v_add_f32_e32 v15, v15, v94
	s_waitcnt lgkmcnt(8)
	v_mfma_f32_32x32x16_bf16 v[16:31], v[6:9], v[80:83], v[16:31]
	v_add_f32_e32 v205, v205, v95
	v_cvt_pk_bf16_f32 v88, v88, v89
	v_cvt_pk_bf16_f32 v89, v90, v91
	v_cvt_pk_bf16_f32 v90, v92, v93
	v_cvt_pk_bf16_f32 v91, v94, v95
	s_waitcnt lgkmcnt(0)
	s_barrier
	s_nop 1
	v_mfma_f32_32x32x16_bf16 v[64:79], v[10:13], v[88:91], v[64:79]
	s_waitcnt vmcnt(7)
	ds_write_b128 v180, v[128:131]
	s_waitcnt vmcnt(6)
	ds_write_b128 v180, v[132:135] offset:18432
	v_mfma_f32_32x32x16_bf16 v[48:63], v[222:225], v[88:91], v[48:63]
	s_waitcnt vmcnt(5)
	ds_write_b128 v182, v[136:139]
	s_waitcnt vmcnt(4)
	ds_write_b128 v182, v[140:143] offset:18432
	v_mfma_f32_32x32x16_bf16 v[32:47], v[226:229], v[88:91], v[32:47]
	s_waitcnt vmcnt(3)
	ds_write_b128 v184, v[144:147]
	s_waitcnt vmcnt(2)
	ds_write_b128 v184, v[148:151] offset:18432
	v_mfma_f32_32x32x16_bf16 v[16:31], v[2:5], v[88:91], v[16:31]
	s_waitcnt vmcnt(1)
	ds_write_b128 v186, v[152:155]
	s_waitcnt vmcnt(0)
	ds_write_b128 v186, v[156:159] offset:18432
	v_add_f32_e32 v15, v15, v205
	s_add_u32 s36, s36, 0x80
	s_addc_u32 s37, s37, 0
	s_add_i32 s38, s38, 64
	s_add_i32 s92, s92, 64
	v_fma_f32 v203, v203, v0, v15
	v_add_u32_e32 v199, 64, v199
	s_mov_b32 s39, s93
	s_waitcnt lgkmcnt(0)
	s_barrier
	s_branch .LBB0_591
